# strategy 4: one static s_setprio 1 for waves 4-7 set once before the step loop, no other setprio in the kernel
# baseline (speedup 1.0000x reference)
; __global__ void __launch_bounds__(NTHR, 2) trunk_fwd(Args args) {
;     ...
;     grid.sync();
;     constexpr int NREP = (REPMASK || REPSYNC) ? 2 : 1;
;     for (int it_ = 0; it_ < 32 * NREP; ++it_) {
.LBB0_861:
	v_readfirstlane_b32 s0, v230
	s_nop 3
	s_cmpk_ge_u32 s0, 0x100
	s_cbranch_scc0 .Lprio_done
	s_setprio 1
